# P9 K/Q epilogue: head-norm gain loads hoisted to epilogue start (were two serialized exposed loads after the barrier)
# baseline (speedup 1.0000x reference)
.LBB0_729:
	v_mov_b32_e32 v184, 1.0
	v_mov_b32_e32 v188, 0
	v_cmp_ne_u32_e32 vcc, 0, v128
	v_cmp_eq_u32_e64 s[8:9], 0, v128
	s_lshr_b32 s98, s50, 1
	s_add_i32 s99, s50, -6
	s_lshr_b32 s99, s99, 2
	s_and_b64 s[100:101], s[62:63], exec
	s_cselect_b32 s98, s98, s99
	s_cselect_b32 s99, 0, 0x600
	s_lshl_b32 s98, s98, 9
	s_add_i32 s98, s98, s99
	s_add_u32 s100, s82, s98
	s_addc_u32 s101, s83, 0
	v_add_u32_e32 v224, s80, v239
	v_mov_b32_e32 v225, s78
	v_cndmask_b32_e64 v226, v224, v225, s[8:9]
	v_or_b32_e32 v224, 4, v224
	v_mov_b32_e32 v225, s81
	v_cndmask_b32_e64 v227, v224, v225, s[8:9]
	v_lshlrev_b32_e32 v226, 2, v226
	v_lshlrev_b32_e32 v227, 2, v227
	global_load_dwordx4 v[152:155], v226, s[100:101]
	global_load_dwordx4 v[156:159], v227, s[100:101]
	v_mov_b32_e32 v192, 0
	v_mov_b32_e32 v193, v188
	v_mov_b32_e32 v194, 0
	v_mov_b32_e32 v195, 0
	v_mov_b32_e32 v196, 1.0
	v_mov_b32_e32 v197, v184
	v_mov_b32_e32 v198, 1.0
	v_mov_b32_e32 v199, 1.0
	s_and_saveexec_b64 s[64:65], s[8:9]
	s_cbranch_execz .LBB0_731
	v_ashrrev_i32_e32 v219, 31, v218
	v_lshlrev_b64 v[128:129], 6, v[218:219]
	v_lshl_add_u64 v[130:131], s[18:19], 0, v[128:129]
	v_lshl_add_u64 v[128:129], s[20:21], 0, v[128:129]
	global_load_dwordx4 v[196:199], v[130:131], off
	global_load_dwordx4 v[192:195], v[128:129], off

.LBB0_745:
	s_or_b64 exec, exec, s[64:65]
	v_ashrrev_i32_e32 v219, 31, v218
	v_lshl_add_u64 v[202:203], v[218:219], 2, s[10:11]
	global_load_dword v200, v[202:203], off sc1
	global_load_dword v249, v[202:203], off offset:64 sc1
	global_load_dword v248, v[202:203], off offset:128 sc1
	global_load_dword v247, v[202:203], off offset:192 sc1
	global_load_dword v246, v[202:203], off offset:512 sc1
	global_load_dword v245, v[202:203], off offset:576 sc1
	global_load_dword v241, v[202:203], off offset:640 sc1
	global_load_dword v219, v[202:203], off offset:704 sc1
	v_mul_f32_e32 v202, v125, v125
	v_mul_f32_e32 v203, v127, v127
	v_fmac_f32_e32 v202, v124, v124
	v_fmac_f32_e32 v203, v126, v126
	v_add_f32_e32 v202, v202, v203
	v_mul_f32_e32 v203, v121, v121
	v_fmac_f32_e32 v203, v120, v120
	v_add_f32_e32 v202, v202, v203
	v_mul_f32_e32 v203, v123, v123
	v_fmac_f32_e32 v203, v122, v122
	v_add_f32_e32 v202, v203, v202
	v_mov_b32_e32 v203, v202
	s_nop 1
	v_permlane16_swap_b32_e32 v202, v203
	v_add_f32_e32 v203, v202, v203
	v_lshlrev_b32_e32 v250, 5, v240
	v_mov_b32_e32 v204, v203
	s_nop 1
	v_permlane32_swap_b32_e32 v203, v204
	v_add_u32_e32 v202, s79, v250
	s_and_saveexec_b64 s[60:61], s[8:9]
	v_add_f32_e32 v203, v203, v204
	ds_write_b32 v202, v203
	s_or_b64 exec, exec, s[60:61]
	v_mul_f32_e32 v203, v105, v105
	v_mul_f32_e32 v204, v107, v107
	v_fmac_f32_e32 v203, v104, v104
	v_fmac_f32_e32 v204, v106, v106
	v_add_f32_e32 v203, v203, v204
	v_mul_f32_e32 v204, v97, v97
	v_fmac_f32_e32 v204, v96, v96
	v_add_f32_e32 v203, v203, v204
	v_mul_f32_e32 v204, v99, v99
	v_fmac_f32_e32 v204, v98, v98
	v_add_f32_e32 v203, v204, v203
	v_mov_b32_e32 v204, v203
	s_nop 1
	v_permlane16_swap_b32_e32 v203, v204
	v_add_f32_e32 v203, v203, v204
	v_mov_b32_e32 v204, v203
	s_nop 1
	v_permlane32_swap_b32_e32 v203, v204
	s_and_saveexec_b64 s[60:61], s[8:9]
	v_add_f32_e32 v203, v203, v204
	ds_write_b32 v202, v203 offset:16
	s_or_b64 exec, exec, s[60:61]
	v_mul_f32_e32 v203, v117, v117
	v_mul_f32_e32 v204, v119, v119
	v_fmac_f32_e32 v203, v116, v116
	v_fmac_f32_e32 v204, v118, v118
	v_add_f32_e32 v203, v203, v204
	v_mul_f32_e32 v204, v113, v113
	v_fmac_f32_e32 v204, v112, v112
	v_add_f32_e32 v203, v203, v204
	v_mul_f32_e32 v204, v115, v115
	v_fmac_f32_e32 v204, v114, v114
	v_add_f32_e32 v203, v204, v203
	v_mov_b32_e32 v204, v203
	s_nop 1
	v_permlane16_swap_b32_e32 v203, v204
	v_add_f32_e32 v203, v203, v204
	v_mov_b32_e32 v204, v203
	s_nop 1
	v_permlane32_swap_b32_e32 v203, v204
	s_and_saveexec_b64 s[60:61], s[8:9]
	v_add_f32_e32 v203, v203, v204
	ds_write_b32 v202, v203 offset:512
	s_or_b64 exec, exec, s[60:61]
	v_mul_f32_e32 v203, v89, v89
	v_mul_f32_e32 v204, v91, v91
	v_fmac_f32_e32 v203, v88, v88
	v_fmac_f32_e32 v204, v90, v90
	v_add_f32_e32 v203, v203, v204
	v_mul_f32_e32 v204, v85, v85
	v_fmac_f32_e32 v204, v84, v84
	v_add_f32_e32 v203, v203, v204
	v_mul_f32_e32 v204, v87, v87
	v_fmac_f32_e32 v204, v86, v86
	v_add_f32_e32 v203, v204, v203
	v_mov_b32_e32 v204, v203
	s_nop 1
	v_permlane16_swap_b32_e32 v203, v204
	v_add_f32_e32 v203, v203, v204
	v_mov_b32_e32 v204, v203
	s_nop 1
	v_permlane32_swap_b32_e32 v203, v204
	s_and_saveexec_b64 s[60:61], s[8:9]
	v_add_f32_e32 v203, v203, v204
	ds_write_b32 v202, v203 offset:528
	s_or_b64 exec, exec, s[60:61]
	v_mul_f32_e32 v203, v109, v109
	v_mul_f32_e32 v204, v111, v111
	v_fmac_f32_e32 v203, v108, v108
	v_fmac_f32_e32 v204, v110, v110
	v_add_f32_e32 v203, v203, v204
	v_mul_f32_e32 v204, v101, v101
	v_fmac_f32_e32 v204, v100, v100
	v_add_f32_e32 v203, v203, v204
	v_mul_f32_e32 v204, v103, v103
	v_fmac_f32_e32 v204, v102, v102
	v_add_f32_e32 v203, v204, v203
	v_mov_b32_e32 v204, v203
	s_nop 1
	v_permlane16_swap_b32_e32 v203, v204
	v_add_f32_e32 v203, v203, v204
	v_mov_b32_e32 v204, v203
	s_nop 1
	v_permlane32_swap_b32_e32 v203, v204
	s_and_saveexec_b64 s[60:61], s[8:9]
	v_add_f32_e32 v203, v203, v204
	ds_write_b32 v202, v203 offset:1024
	s_or_b64 exec, exec, s[60:61]
	v_mul_f32_e32 v203, v77, v77
	v_mul_f32_e32 v204, v79, v79
	v_fmac_f32_e32 v203, v76, v76
	v_fmac_f32_e32 v204, v78, v78
	v_add_f32_e32 v203, v203, v204
	v_mul_f32_e32 v204, v73, v73
	v_fmac_f32_e32 v204, v72, v72
	v_add_f32_e32 v203, v203, v204
	v_mul_f32_e32 v204, v75, v75
	v_fmac_f32_e32 v204, v74, v74
	v_add_f32_e32 v203, v204, v203
	v_mov_b32_e32 v204, v203
	s_nop 1
	v_permlane16_swap_b32_e32 v203, v204
	v_add_f32_e32 v203, v203, v204
	v_mov_b32_e32 v204, v203
	s_nop 1
	v_permlane32_swap_b32_e32 v203, v204
	s_and_saveexec_b64 s[60:61], s[8:9]
	v_add_f32_e32 v203, v203, v204
	ds_write_b32 v202, v203 offset:1040
	s_or_b64 exec, exec, s[60:61]
	v_mul_f32_e32 v203, v93, v93
	v_mul_f32_e32 v204, v95, v95
	v_fmac_f32_e32 v203, v92, v92
	v_fmac_f32_e32 v204, v94, v94
	v_add_f32_e32 v203, v203, v204
	v_mul_f32_e32 v204, v81, v81
	v_fmac_f32_e32 v204, v80, v80
	v_add_f32_e32 v203, v203, v204
	v_mul_f32_e32 v204, v83, v83
	v_fmac_f32_e32 v204, v82, v82
	v_add_f32_e32 v203, v204, v203
	v_mov_b32_e32 v204, v203
	s_nop 1
	v_permlane16_swap_b32_e32 v203, v204
	v_add_f32_e32 v203, v203, v204
	v_mov_b32_e32 v204, v203
	s_nop 1
	v_permlane32_swap_b32_e32 v203, v204
	s_and_saveexec_b64 s[60:61], s[8:9]
	v_add_f32_e32 v203, v203, v204
	ds_write_b32 v202, v203 offset:1536
	s_or_b64 exec, exec, s[60:61]
	v_mul_f32_e32 v203, v69, v69
	v_mul_f32_e32 v204, v71, v71
	v_fmac_f32_e32 v203, v68, v68
	v_fmac_f32_e32 v204, v70, v70
	v_add_f32_e32 v203, v203, v204
	v_mul_f32_e32 v204, v65, v65
	v_fmac_f32_e32 v204, v64, v64
	v_add_f32_e32 v203, v203, v204
	v_mul_f32_e32 v204, v67, v67
	v_fmac_f32_e32 v204, v66, v66
	v_add_f32_e32 v203, v204, v203
	v_mov_b32_e32 v204, v203
	s_nop 1
	v_permlane16_swap_b32_e32 v203, v204
	v_add_f32_e32 v203, v203, v204
	v_mov_b32_e32 v204, v203
	s_nop 1
	v_permlane32_swap_b32_e32 v203, v204
	s_and_saveexec_b64 s[60:61], s[8:9]
	v_add_f32_e32 v203, v203, v204
	ds_write_b32 v202, v203 offset:1552
	s_or_b64 exec, exec, s[60:61]
	v_mul_f32_e32 v203, v61, v61
	v_mul_f32_e32 v204, v63, v63
	v_fmac_f32_e32 v203, v60, v60
	v_fmac_f32_e32 v204, v62, v62
	v_add_f32_e32 v203, v203, v204
	v_mul_f32_e32 v204, v57, v57
	v_fmac_f32_e32 v204, v56, v56
	v_add_f32_e32 v203, v203, v204
	v_mul_f32_e32 v204, v59, v59
	v_fmac_f32_e32 v204, v58, v58
	v_add_f32_e32 v203, v204, v203
	v_mov_b32_e32 v204, v203
	s_nop 1
	v_permlane16_swap_b32_e32 v203, v204
	v_add_f32_e32 v203, v203, v204
	v_mov_b32_e32 v204, v203
	s_nop 1
	v_permlane32_swap_b32_e32 v203, v204
	s_and_saveexec_b64 s[60:61], s[8:9]
	v_add_f32_e32 v203, v203, v204
	ds_write_b32 v202, v203 offset:4096
	s_or_b64 exec, exec, s[60:61]
	v_mul_f32_e32 v203, v53, v53
	v_mul_f32_e32 v204, v55, v55
	v_fmac_f32_e32 v203, v52, v52
	v_fmac_f32_e32 v204, v54, v54
	v_add_f32_e32 v203, v203, v204
	v_mul_f32_e32 v204, v45, v45
	v_fmac_f32_e32 v204, v44, v44
	v_add_f32_e32 v203, v203, v204
	v_mul_f32_e32 v204, v47, v47
	v_fmac_f32_e32 v204, v46, v46
	v_add_f32_e32 v203, v204, v203
	v_mov_b32_e32 v204, v203
	s_nop 1
	v_permlane16_swap_b32_e32 v203, v204
	v_add_f32_e32 v203, v203, v204
	v_mov_b32_e32 v204, v203
	s_nop 1
	v_permlane32_swap_b32_e32 v203, v204
	s_and_saveexec_b64 s[60:61], s[8:9]
	v_add_f32_e32 v203, v203, v204
	ds_write_b32 v202, v203 offset:4112
	s_or_b64 exec, exec, s[60:61]
	v_mul_f32_e32 v203, v49, v49
	v_mul_f32_e32 v204, v51, v51
	v_fmac_f32_e32 v203, v48, v48
	v_fmac_f32_e32 v204, v50, v50
	v_add_f32_e32 v203, v203, v204
	v_mul_f32_e32 v204, v41, v41
	v_fmac_f32_e32 v204, v40, v40
	v_add_f32_e32 v203, v203, v204
	v_mul_f32_e32 v204, v43, v43
	v_fmac_f32_e32 v204, v42, v42
	v_add_f32_e32 v203, v204, v203
	v_mov_b32_e32 v204, v203
	s_nop 1
	v_permlane16_swap_b32_e32 v203, v204
	v_add_f32_e32 v203, v203, v204
	v_mov_b32_e32 v204, v203
	s_nop 1
	v_permlane32_swap_b32_e32 v203, v204
	s_and_saveexec_b64 s[60:61], s[8:9]
	v_add_f32_e32 v203, v203, v204
	ds_write_b32 v202, v203 offset:4608
	s_or_b64 exec, exec, s[60:61]
	v_mul_f32_e32 v203, v37, v37
	v_mul_f32_e32 v204, v39, v39
	v_fmac_f32_e32 v203, v36, v36
	v_fmac_f32_e32 v204, v38, v38
	v_add_f32_e32 v203, v203, v204
	v_mul_f32_e32 v204, v29, v29
	v_fmac_f32_e32 v204, v28, v28
	v_add_f32_e32 v203, v203, v204
	v_mul_f32_e32 v204, v31, v31
	v_fmac_f32_e32 v204, v30, v30
	v_add_f32_e32 v203, v204, v203
	v_mov_b32_e32 v204, v203
	s_nop 1
	v_permlane16_swap_b32_e32 v203, v204
	v_add_f32_e32 v203, v203, v204
	v_mov_b32_e32 v204, v203
	s_nop 1
	v_permlane32_swap_b32_e32 v203, v204
	s_and_saveexec_b64 s[60:61], s[8:9]
	v_add_f32_e32 v203, v203, v204
	ds_write_b32 v202, v203 offset:4624
	s_or_b64 exec, exec, s[60:61]
	v_mul_f32_e32 v203, v33, v33
	v_mul_f32_e32 v204, v35, v35
	v_fmac_f32_e32 v203, v32, v32
	v_fmac_f32_e32 v204, v34, v34
	v_add_f32_e32 v203, v203, v204
	v_mul_f32_e32 v204, v25, v25
	v_fmac_f32_e32 v204, v24, v24
	v_add_f32_e32 v203, v203, v204
	v_mul_f32_e32 v204, v27, v27
	v_fmac_f32_e32 v204, v26, v26
	v_add_f32_e32 v203, v204, v203
	v_mov_b32_e32 v204, v203
	s_nop 1
	v_permlane16_swap_b32_e32 v203, v204
	v_add_f32_e32 v203, v203, v204
	v_mov_b32_e32 v204, v203
	s_nop 1
	v_permlane32_swap_b32_e32 v203, v204
	s_and_saveexec_b64 s[60:61], s[8:9]
	v_add_f32_e32 v203, v203, v204
	ds_write_b32 v202, v203 offset:5120
	s_or_b64 exec, exec, s[60:61]
	v_mul_f32_e32 v203, v21, v21
	v_mul_f32_e32 v204, v23, v23
	v_fmac_f32_e32 v203, v20, v20
	v_fmac_f32_e32 v204, v22, v22
	v_add_f32_e32 v203, v203, v204
	v_mul_f32_e32 v204, v13, v13
	v_fmac_f32_e32 v204, v12, v12
	v_add_f32_e32 v203, v203, v204
	v_mul_f32_e32 v204, v15, v15
	v_fmac_f32_e32 v204, v14, v14
	v_add_f32_e32 v203, v204, v203
	v_mov_b32_e32 v204, v203
	s_nop 1
	v_permlane16_swap_b32_e32 v203, v204
	v_add_f32_e32 v203, v203, v204
	v_mov_b32_e32 v204, v203
	s_nop 1
	v_permlane32_swap_b32_e32 v203, v204
	s_and_saveexec_b64 s[60:61], s[8:9]
	v_add_f32_e32 v203, v203, v204
	ds_write_b32 v202, v203 offset:5136
	s_or_b64 exec, exec, s[60:61]
	v_mul_f32_e32 v203, v17, v17
	v_mul_f32_e32 v204, v19, v19
	v_fmac_f32_e32 v203, v16, v16
	v_fmac_f32_e32 v204, v18, v18
	v_add_f32_e32 v203, v203, v204
	v_mul_f32_e32 v204, v9, v9
	v_fmac_f32_e32 v204, v8, v8
	v_add_f32_e32 v203, v203, v204
	v_mul_f32_e32 v204, v11, v11
	v_fmac_f32_e32 v204, v10, v10
	v_add_f32_e32 v203, v204, v203
	v_mov_b32_e32 v204, v203
	s_nop 1
	v_permlane16_swap_b32_e32 v203, v204
	v_add_f32_e32 v203, v203, v204
	v_mov_b32_e32 v204, v203
	s_nop 1
	v_permlane32_swap_b32_e32 v203, v204
	s_and_saveexec_b64 s[60:61], s[8:9]
	v_add_f32_e32 v203, v203, v204
	ds_write_b32 v202, v203 offset:5632
	s_or_b64 exec, exec, s[60:61]
	v_mul_f32_e32 v203, v5, v5
	v_mul_f32_e32 v204, v7, v7
	v_fmac_f32_e32 v203, v4, v4
	v_fmac_f32_e32 v204, v6, v6
	v_add_f32_e32 v203, v203, v204
	v_mul_f32_e32 v204, v1, v1
	v_fmac_f32_e32 v204, v0, v0
	v_add_f32_e32 v203, v203, v204
	v_mul_f32_e32 v204, v3, v3
	v_fmac_f32_e32 v204, v2, v2
	v_add_f32_e32 v203, v204, v203
	v_mov_b32_e32 v204, v203
	s_nop 1
	v_permlane16_swap_b32_e32 v203, v204
	v_add_f32_e32 v203, v203, v204
	v_mov_b32_e32 v204, v203
	s_nop 1
	v_permlane32_swap_b32_e32 v203, v204
	s_and_saveexec_b64 s[60:61], s[8:9]
	v_add_f32_e32 v203, v203, v204
	ds_write_b32 v202, v203 offset:5648
	s_or_b64 exec, exec, s[60:61]
	s_and_b64 s[60:61], s[62:63], exec
	s_cselect_b32 s60, s92, 0xc00
	s_lshr_b32 s61, s50, 1
	s_add_i32 s50, s50, -6
	s_lshr_b32 s64, s50, 2
	s_and_b64 s[50:51], s[62:63], exec
	s_cselect_b32 s61, s61, s64
	s_add_i32 s64, s39, 0xfffffa00
	v_add_u32_e32 v202, s80, v239
	v_mov_b32_e32 v203, s78
	s_and_b64 s[50:51], s[62:63], exec
	v_cndmask_b32_e64 v222, v202, v203, s[8:9]
	v_or_b32_e32 v202, 4, v202
	v_mov_b32_e32 v203, s81
	v_cndmask_b32_e64 v220, v202, v203, s[8:9]
	s_cselect_b32 s8, 0, 0x600
	s_cselect_b32 s50, s39, s64
	s_add_u32 s51, s82, s8
	s_addc_u32 s64, s83, 0
	s_lshl_b32 s8, s61, 7
	s_ashr_i32 s9, s8, 31
	s_lshl_b64 s[8:9], s[8:9], 2
	s_add_u32 s8, s51, s8
	s_addc_u32 s9, s64, s9
	v_ashrrev_i32_e32 v223, 31, v222
	v_ashrrev_i32_e32 v221, 31, v220
	s_waitcnt lgkmcnt(0)
	s_barrier
	s_waitcnt vmcnt(0)
	v_fmamk_f32 v204, v200, 0x3a800000, v238
	v_add_u32_e32 v200, 0x20000, v250
	ds_read_b128 v[200:203], v200
	v_mul_f32_e32 v251, 0x358637bd, v204
	v_mov_b32_e32 v205, 0x3e0293ee
	v_cndmask_b32_e64 v244, v205, 1.0, s[62:63]
	v_mad_i64_i32 v[204:205], s[8:9], s60, v218, 0
	s_waitcnt lgkmcnt(0)
	v_mov_b32_e32 v224, v201
	v_mov_b32_e32 v225, v202
	v_mov_b32_e32 v201, v203
	v_pk_add_f32 v[200:201], v[224:225], v[200:201]
	s_ashr_i32 s51, s50, 31
	v_add_f32_e32 v200, v200, v201
	v_fmamk_f32 v200, v200, 0x3c000000, v251
	v_rsq_f32_e32 v200, v200
	s_lshl_b64 s[8:9], s[50:51], 1
	s_add_u32 s8, s48, s8
	s_addc_u32 s9, s49, s9
	v_mul_f32_e32 v200, v244, v200
	v_pk_mul_f32 v[202:203], v[124:125], v[200:201] op_sel_hi:[1,0]
	v_pk_mul_f32 v[226:227], v[126:127], v[200:201] op_sel_hi:[1,0]
	v_pk_mul_f32 v[252:253], v[120:121], v[200:201] op_sel_hi:[1,0]
	v_pk_mul_f32 v[200:201], v[122:123], v[200:201] op_sel_hi:[1,0]
	v_lshl_add_u64 v[230:231], v[204:205], 1, s[8:9]
	v_lshl_add_u64 v[224:225], v[222:223], 1, v[230:231]
	v_pk_mul_f32 v[228:229], v[154:155], v[226:227]
	v_pk_mul_f32 v[202:203], v[152:153], v[202:203]
	v_pk_mul_f32 v[226:227], v[158:159], v[200:201]
	v_pk_mul_f32 v[200:201], v[156:157], v[252:253]
	s_and_saveexec_b64 s[50:51], vcc
	s_xor_b64 s[50:51], exec, s[50:51]
	s_cbranch_execz .LBB0_779
	v_cvt_pk_bf16_f32 v202, v202, v203
	v_cvt_pk_bf16_f32 v203, v228, v229
	v_cvt_pk_bf16_f32 v204, v200, v201
	v_cvt_pk_bf16_f32 v205, v226, v227
	global_store_dwordx4 v[224:225], v[202:205], off
